# scan phase: all 32 chunk loads kept in flight with counted waits (was 4 x load-batch/vmcnt(0)); stacked on the max3 row-max trees
# baseline (speedup 1.0000x reference)
; __device__ __forceinline__ unsigned pk_bf16(float lo, float hi) { f32x2 v = {lo, hi}; bf16x2_t b = __builtin_convertvector(v, bf16x2_t); return __builtin_bit_cast(unsigned, b); }
; __device__ __forceinline__ void gla_scan_phase(const Ctx& c) {
;     const float* DST = (const float*)(c.ws + WS_DST); const float* EL = (const float*)(c.ws + WS_EL); bf16_t* SBT = (bf16_t*)(c.ws + WS_SBT);
;     for (int idx = c.gw * 64 + c.lane; idx < 16 * 8192; idx += c.NGW * 64) {
;         const int bh = idx >> 13, e = idx & 8191, k = e & 63;
;         float S = 0.f;
; #pragma unroll 8
;         for (int ch = 0; ch < 32; ++ch) {
;             const size_t o = (size_t)(bh * 32 + ch) * 8192 + e;
;             SBT[o] = (bf16_t)(pk_bf16(S, 0.f) & 0xffffu);
;             S = EL[(size_t)(bh * 32 + ch) * 64 + k] * (S + DST[o]);
;         }
;     }
.LBB0_536:
	s_add_u32 s6, s48, 0x2b300000
	s_addc_u32 s7, s49, 0
	s_add_u32 s12, s6, 0x1000
	s_addc_u32 s13, s7, 0
	s_add_u32 s8, s48, 0x2c500000
	s_addc_u32 s9, s49, 0
	s_add_u32 s10, s48, 0x2d500000
	s_addc_u32 s11, s49, 0
	global_load_dword v30, v2, s[6:7]
	global_load_dword v62, v4, s[8:9]
	s_add_u32 s8, s8, 0x8000
	s_addc_u32 s9, s9, 0
	global_load_dword v31, v2, s[6:7] offset:256
	global_load_dword v63, v4, s[8:9]
	s_add_u32 s8, s8, 0x8000
	s_addc_u32 s9, s9, 0
	global_load_dword v32, v2, s[6:7] offset:512
	global_load_dword v64, v4, s[8:9]
	s_add_u32 s8, s8, 0x8000
	s_addc_u32 s9, s9, 0
	global_load_dword v33, v2, s[6:7] offset:768
	global_load_dword v65, v4, s[8:9]
	s_add_u32 s8, s8, 0x8000
	s_addc_u32 s9, s9, 0
	global_load_dword v34, v2, s[6:7] offset:1024
	global_load_dword v66, v4, s[8:9]
	s_add_u32 s8, s8, 0x8000
	s_addc_u32 s9, s9, 0
	global_load_dword v35, v2, s[6:7] offset:1280
	global_load_dword v67, v4, s[8:9]
	s_add_u32 s8, s8, 0x8000
	s_addc_u32 s9, s9, 0
	global_load_dword v36, v2, s[6:7] offset:1536
	global_load_dword v68, v4, s[8:9]
	s_add_u32 s8, s8, 0x8000
	s_addc_u32 s9, s9, 0
	global_load_dword v37, v2, s[6:7] offset:1792
	global_load_dword v69, v4, s[8:9]
	s_add_u32 s8, s8, 0x8000
	s_addc_u32 s9, s9, 0
	global_load_dword v38, v2, s[6:7] offset:2048
	global_load_dword v70, v4, s[8:9]
	s_add_u32 s8, s8, 0x8000
	s_addc_u32 s9, s9, 0
	global_load_dword v39, v2, s[6:7] offset:2304
	global_load_dword v71, v4, s[8:9]
	s_add_u32 s8, s8, 0x8000
	s_addc_u32 s9, s9, 0
	global_load_dword v40, v2, s[6:7] offset:2560
	global_load_dword v72, v4, s[8:9]
	s_add_u32 s8, s8, 0x8000
	s_addc_u32 s9, s9, 0
	global_load_dword v41, v2, s[6:7] offset:2816
	global_load_dword v73, v4, s[8:9]
	s_add_u32 s8, s8, 0x8000
	s_addc_u32 s9, s9, 0
	global_load_dword v42, v2, s[6:7] offset:3072
	global_load_dword v74, v4, s[8:9]
	s_add_u32 s8, s8, 0x8000
	s_addc_u32 s9, s9, 0
	global_load_dword v43, v2, s[6:7] offset:3328
	global_load_dword v75, v4, s[8:9]
	s_add_u32 s8, s8, 0x8000
	s_addc_u32 s9, s9, 0
	global_load_dword v44, v2, s[6:7] offset:3584
	global_load_dword v76, v4, s[8:9]
	s_add_u32 s8, s8, 0x8000
	s_addc_u32 s9, s9, 0
	global_load_dword v45, v2, s[6:7] offset:3840
	global_load_dword v77, v4, s[8:9]
	s_add_u32 s8, s8, 0x8000
	s_addc_u32 s9, s9, 0
	v_cvt_pk_bf16_f32 v15, v10, 0
	global_store_short v6, v15, s[10:11]
	s_add_u32 s10, s10, 0x4000
	s_addc_u32 s11, s11, 0
	s_waitcnt vmcnt(31)
	v_add_f32_e32 v62, v10, v62
	global_load_dword v46, v2, s[12:13]
	global_load_dword v78, v4, s[8:9]
	s_add_u32 s8, s8, 0x8000
	s_addc_u32 s9, s9, 0
	v_mul_f32_e32 v10, v30, v62
	v_cvt_pk_bf16_f32 v15, v10, 0
	global_store_short v6, v15, s[10:11]
	s_add_u32 s10, s10, 0x4000
	s_addc_u32 s11, s11, 0
	s_waitcnt vmcnt(32)
	v_fmac_f32_e32 v63, v30, v62
	global_load_dword v47, v2, s[12:13] offset:256
	global_load_dword v79, v4, s[8:9]
	s_add_u32 s8, s8, 0x8000
	s_addc_u32 s9, s9, 0
	v_mul_f32_e32 v10, v31, v63
	v_cvt_pk_bf16_f32 v15, v10, 0
	global_store_short v6, v15, s[10:11]
	s_add_u32 s10, s10, 0x4000
	s_addc_u32 s11, s11, 0
	s_waitcnt vmcnt(33)
	v_fmac_f32_e32 v64, v31, v63
	global_load_dword v48, v2, s[12:13] offset:512
	global_load_dword v80, v4, s[8:9]
	s_add_u32 s8, s8, 0x8000
	s_addc_u32 s9, s9, 0
	v_mul_f32_e32 v10, v32, v64
	v_cvt_pk_bf16_f32 v15, v10, 0
	global_store_short v6, v15, s[10:11]
	s_add_u32 s10, s10, 0x4000
	s_addc_u32 s11, s11, 0
	s_waitcnt vmcnt(34)
	v_fmac_f32_e32 v65, v32, v64
	global_load_dword v49, v2, s[12:13] offset:768
	global_load_dword v81, v4, s[8:9]
	s_add_u32 s8, s8, 0x8000
	s_addc_u32 s9, s9, 0
	v_mul_f32_e32 v10, v33, v65
	v_cvt_pk_bf16_f32 v15, v10, 0
	global_store_short v6, v15, s[10:11]
	s_add_u32 s10, s10, 0x4000
	s_addc_u32 s11, s11, 0
	s_waitcnt vmcnt(35)
	v_fmac_f32_e32 v66, v33, v65
	global_load_dword v50, v2, s[12:13] offset:1024
	global_load_dword v82, v4, s[8:9]
	s_add_u32 s8, s8, 0x8000
	s_addc_u32 s9, s9, 0
	v_mul_f32_e32 v10, v34, v66
	v_cvt_pk_bf16_f32 v15, v10, 0
	global_store_short v6, v15, s[10:11]
	s_add_u32 s10, s10, 0x4000
	s_addc_u32 s11, s11, 0
	s_waitcnt vmcnt(36)
	v_fmac_f32_e32 v67, v34, v66
	global_load_dword v51, v2, s[12:13] offset:1280
	global_load_dword v83, v4, s[8:9]
	s_add_u32 s8, s8, 0x8000
	s_addc_u32 s9, s9, 0
	v_mul_f32_e32 v10, v35, v67
	v_cvt_pk_bf16_f32 v15, v10, 0
	global_store_short v6, v15, s[10:11]
	s_add_u32 s10, s10, 0x4000
	s_addc_u32 s11, s11, 0
	s_waitcnt vmcnt(37)
	v_fmac_f32_e32 v68, v35, v67
	global_load_dword v52, v2, s[12:13] offset:1536
	global_load_dword v84, v4, s[8:9]
	s_add_u32 s8, s8, 0x8000
	s_addc_u32 s9, s9, 0
	v_mul_f32_e32 v10, v36, v68
	v_cvt_pk_bf16_f32 v15, v10, 0
	global_store_short v6, v15, s[10:11]
	s_add_u32 s10, s10, 0x4000
	s_addc_u32 s11, s11, 0
	s_waitcnt vmcnt(38)
	v_fmac_f32_e32 v69, v36, v68
	global_load_dword v53, v2, s[12:13] offset:1792
	global_load_dword v85, v4, s[8:9]
	s_add_u32 s8, s8, 0x8000
	s_addc_u32 s9, s9, 0
	v_mul_f32_e32 v10, v37, v69
	v_cvt_pk_bf16_f32 v15, v10, 0
	global_store_short v6, v15, s[10:11]
	s_add_u32 s10, s10, 0x4000
	s_addc_u32 s11, s11, 0
	s_waitcnt vmcnt(39)
	v_add_f32_e32 v70, v10, v70
	global_load_dword v54, v2, s[12:13] offset:2048
	global_load_dword v86, v4, s[8:9]
	s_add_u32 s8, s8, 0x8000
	s_addc_u32 s9, s9, 0
	v_mul_f32_e32 v10, v38, v70
	v_cvt_pk_bf16_f32 v15, v10, 0
	global_store_short v6, v15, s[10:11]
	s_add_u32 s10, s10, 0x4000
	s_addc_u32 s11, s11, 0
	s_waitcnt vmcnt(40)
; __device__ __forceinline__ unsigned pk_bf16(float lo, float hi) { f32x2 v = {lo, hi}; bf16x2_t b = __builtin_convertvector(v, bf16x2_t); return __builtin_bit_cast(unsigned, b); }
; __device__ __forceinline__ void gla_scan_phase(const Ctx& c) {
;     const float* DST = (const float*)(c.ws + WS_DST); const float* EL = (const float*)(c.ws + WS_EL); bf16_t* SBT = (bf16_t*)(c.ws + WS_SBT);
;     for (int idx = c.gw * 64 + c.lane; idx < 16 * 8192; idx += c.NGW * 64) {
;         const int bh = idx >> 13, e = idx & 8191, k = e & 63;
;         float S = 0.f;
; #pragma unroll 8
;         for (int ch = 0; ch < 32; ++ch) {
;             const size_t o = (size_t)(bh * 32 + ch) * 8192 + e;
;             SBT[o] = (bf16_t)(pk_bf16(S, 0.f) & 0xffffu);
;             S = EL[(size_t)(bh * 32 + ch) * 64 + k] * (S + DST[o]);
;         }
;     }
	v_fmac_f32_e32 v71, v38, v70
	global_load_dword v55, v2, s[12:13] offset:2304
	global_load_dword v87, v4, s[8:9]
	s_add_u32 s8, s8, 0x8000
	s_addc_u32 s9, s9, 0
	v_mul_f32_e32 v10, v39, v71
	v_cvt_pk_bf16_f32 v15, v10, 0
	global_store_short v6, v15, s[10:11]
	s_add_u32 s10, s10, 0x4000
	s_addc_u32 s11, s11, 0
	s_waitcnt vmcnt(41)
	v_fmac_f32_e32 v72, v39, v71
	global_load_dword v56, v2, s[12:13] offset:2560
	global_load_dword v88, v4, s[8:9]
	s_add_u32 s8, s8, 0x8000
	s_addc_u32 s9, s9, 0
	v_mul_f32_e32 v10, v40, v72
	v_cvt_pk_bf16_f32 v15, v10, 0
	global_store_short v6, v15, s[10:11]
	s_add_u32 s10, s10, 0x4000
	s_addc_u32 s11, s11, 0
	s_waitcnt vmcnt(42)
	v_fmac_f32_e32 v73, v40, v72
	global_load_dword v57, v2, s[12:13] offset:2816
	global_load_dword v89, v4, s[8:9]
	s_add_u32 s8, s8, 0x8000
	s_addc_u32 s9, s9, 0
	v_mul_f32_e32 v10, v41, v73
	v_cvt_pk_bf16_f32 v15, v10, 0
	global_store_short v6, v15, s[10:11]
	s_add_u32 s10, s10, 0x4000
	s_addc_u32 s11, s11, 0
	s_waitcnt vmcnt(43)
	v_fmac_f32_e32 v74, v41, v73
	global_load_dword v58, v2, s[12:13] offset:3072
	global_load_dword v90, v4, s[8:9]
	s_add_u32 s8, s8, 0x8000
	s_addc_u32 s9, s9, 0
	v_mul_f32_e32 v10, v42, v74
	v_cvt_pk_bf16_f32 v15, v10, 0
	global_store_short v6, v15, s[10:11]
	s_add_u32 s10, s10, 0x4000
	s_addc_u32 s11, s11, 0
	s_waitcnt vmcnt(44)
	v_fmac_f32_e32 v75, v42, v74
	global_load_dword v59, v2, s[12:13] offset:3328
	global_load_dword v91, v4, s[8:9]
	s_add_u32 s8, s8, 0x8000
	s_addc_u32 s9, s9, 0
	v_mul_f32_e32 v10, v43, v75
	v_cvt_pk_bf16_f32 v15, v10, 0
	global_store_short v6, v15, s[10:11]
	s_add_u32 s10, s10, 0x4000
	s_addc_u32 s11, s11, 0
	s_waitcnt vmcnt(45)
	v_fmac_f32_e32 v76, v43, v75
	global_load_dword v60, v2, s[12:13] offset:3584
	global_load_dword v92, v4, s[8:9]
	s_add_u32 s8, s8, 0x8000
	s_addc_u32 s9, s9, 0
	v_mul_f32_e32 v10, v44, v76
	v_cvt_pk_bf16_f32 v15, v10, 0
	global_store_short v6, v15, s[10:11]
	s_add_u32 s10, s10, 0x4000
	s_addc_u32 s11, s11, 0
	s_waitcnt vmcnt(46)
	v_fmac_f32_e32 v77, v44, v76
	global_load_dword v61, v2, s[12:13] offset:3840
	global_load_dword v93, v4, s[8:9]
	s_add_u32 s8, s8, 0x8000
	s_addc_u32 s9, s9, 0
	v_mul_f32_e32 v10, v45, v77
	v_cvt_pk_bf16_f32 v15, v10, 0
	global_store_short v6, v15, s[10:11]
	s_add_u32 s10, s10, 0x4000
	s_addc_u32 s11, s11, 0
	s_waitcnt vmcnt(46)
	v_add_f32_e32 v78, v10, v78
	v_mul_f32_e32 v10, v46, v78
	v_cvt_pk_bf16_f32 v15, v10, 0
	global_store_short v6, v15, s[10:11]
	s_add_u32 s10, s10, 0x4000
	s_addc_u32 s11, s11, 0
	s_waitcnt vmcnt(44)
	v_fmac_f32_e32 v79, v46, v78
	v_mul_f32_e32 v10, v47, v79
	v_cvt_pk_bf16_f32 v15, v10, 0
	global_store_short v6, v15, s[10:11]
	s_add_u32 s10, s10, 0x4000
	s_addc_u32 s11, s11, 0
	s_waitcnt vmcnt(42)
	v_fmac_f32_e32 v80, v47, v79
	v_mul_f32_e32 v10, v48, v80
	v_cvt_pk_bf16_f32 v15, v10, 0
	global_store_short v6, v15, s[10:11]
	s_add_u32 s10, s10, 0x4000
	s_addc_u32 s11, s11, 0
	s_waitcnt vmcnt(40)
	v_fmac_f32_e32 v81, v48, v80
	v_mul_f32_e32 v10, v49, v81
	v_cvt_pk_bf16_f32 v15, v10, 0
	global_store_short v6, v15, s[10:11]
	s_add_u32 s10, s10, 0x4000
	s_addc_u32 s11, s11, 0
	s_waitcnt vmcnt(38)
	v_fmac_f32_e32 v82, v49, v81
	v_mul_f32_e32 v10, v50, v82
	v_cvt_pk_bf16_f32 v15, v10, 0
	global_store_short v6, v15, s[10:11]
	s_add_u32 s10, s10, 0x4000
	s_addc_u32 s11, s11, 0
	s_waitcnt vmcnt(36)
	v_fmac_f32_e32 v83, v50, v82
	v_mul_f32_e32 v10, v51, v83
	v_cvt_pk_bf16_f32 v15, v10, 0
	global_store_short v6, v15, s[10:11]
	s_add_u32 s10, s10, 0x4000
	s_addc_u32 s11, s11, 0
	s_waitcnt vmcnt(34)
	v_fmac_f32_e32 v84, v51, v83
	v_mul_f32_e32 v10, v52, v84
	v_cvt_pk_bf16_f32 v15, v10, 0
	global_store_short v6, v15, s[10:11]
	s_add_u32 s10, s10, 0x4000
	s_addc_u32 s11, s11, 0
	s_waitcnt vmcnt(32)
	v_fmac_f32_e32 v85, v52, v84
	v_mul_f32_e32 v10, v53, v85
	v_cvt_pk_bf16_f32 v15, v10, 0
	global_store_short v6, v15, s[10:11]
	s_add_u32 s10, s10, 0x4000
	s_addc_u32 s11, s11, 0
	s_waitcnt vmcnt(30)
	v_add_f32_e32 v86, v10, v86
	v_mul_f32_e32 v10, v54, v86
	v_cvt_pk_bf16_f32 v15, v10, 0
	global_store_short v6, v15, s[10:11]
	s_add_u32 s10, s10, 0x4000
	s_addc_u32 s11, s11, 0
	s_waitcnt vmcnt(28)
	v_fmac_f32_e32 v87, v54, v86
	v_mul_f32_e32 v10, v55, v87
	v_cvt_pk_bf16_f32 v15, v10, 0
	global_store_short v6, v15, s[10:11]
	s_add_u32 s10, s10, 0x4000
	s_addc_u32 s11, s11, 0
	s_waitcnt vmcnt(26)
	v_fmac_f32_e32 v88, v55, v87
	v_mul_f32_e32 v10, v56, v88
	v_cvt_pk_bf16_f32 v15, v10, 0
	global_store_short v6, v15, s[10:11]
	s_add_u32 s10, s10, 0x4000
	s_addc_u32 s11, s11, 0
	s_waitcnt vmcnt(24)
	v_fmac_f32_e32 v89, v56, v88
	v_mul_f32_e32 v10, v57, v89
	v_cvt_pk_bf16_f32 v15, v10, 0
	global_store_short v6, v15, s[10:11]
	s_add_u32 s10, s10, 0x4000
	s_addc_u32 s11, s11, 0
	s_waitcnt vmcnt(22)
	v_fmac_f32_e32 v90, v57, v89
	v_mul_f32_e32 v10, v58, v90
	v_cvt_pk_bf16_f32 v15, v10, 0
	global_store_short v6, v15, s[10:11]
	s_add_u32 s10, s10, 0x4000
	s_addc_u32 s11, s11, 0
	s_waitcnt vmcnt(20)
	v_fmac_f32_e32 v91, v58, v90
	v_mul_f32_e32 v10, v59, v91
	v_cvt_pk_bf16_f32 v15, v10, 0
	global_store_short v6, v15, s[10:11]
	s_add_u32 s10, s10, 0x4000
	s_addc_u32 s11, s11, 0
	s_waitcnt vmcnt(18)
	v_fmac_f32_e32 v92, v59, v91
	v_mul_f32_e32 v10, v60, v92
	v_cvt_pk_bf16_f32 v15, v10, 0
	global_store_short v6, v15, s[10:11]
	s_add_u32 s10, s10, 0x4000
	s_addc_u32 s11, s11, 0
	s_waitcnt vmcnt(16)
	v_fmac_f32_e32 v93, v60, v92
	v_add_u32_e32 v8, s22, v8
	s_mov_b32 s6, 0x1ffff
	v_cmp_lt_i32_e32 vcc, s6, v8
	s_or_b64 s[4:5], vcc, s[4:5]
	v_add_u16_e32 v9, s22, v9
	s_andn2_b64 exec, exec, s[4:5]
	s_cbranch_execnz .LBB0_535
